# v083 plus standalone finalize-A row loop processing four rows per trip (loads of four rows in flight together)
# speedup vs baseline: 1.0052x; 1.0052x over previous
; __device__ __forceinline__ float bf2f(bfu h) { return __uint_as_float(((unsigned)h) << 16); }
; __device__ __forceinline__ unsigned pack2(float a, float b) { return (unsigned)f2bf(a) | ((unsigned)f2bf(b) << 16); }
; __device__ __forceinline__ float frsq(float x) { return __builtin_amdgcn_rsqf(x); }
; __device__ __forceinline__ float siluf_(float x) { return x * frcp(1.0f + fexp(-x)); }
; #define SHX(v, m) shx_((v), (m), lane)
; __device__ void ab_fin_rows(const Params& p, int L, int row0, int nrows, const bool doA, const bool doB) {
;     ...
;   for (int rr = wid; rr < nrows; rr += 8) {
;     const long row = row0 + rr;
;     const int t = (int)(row & (TSEQ - 1));
;     bfu* pr = pab + row * 3584;
;     const int c0 = lane * 8;
;     if (doA) {
;     bf16x8 o = *(const bf16x8*)(pr + c0);
;     bf16x8 z = *(const bf16x8*)(pr + 1536 + c0);
;     float of[8]; float ss = 0.f;
;     for (int e = 0; e < 8; ++e) { of[e] = bf2f((bfu)o[e]); ss += of[e] * of[e]; }
;     ss += SHX(ss, 1); ss += SHX(ss, 2); ss += SHX(ss, 4); ss += SHX(ss, 8);
;     const float rs = frsq(ss * (1.0f / 128.0f) + 1e-6f);
;     float ra[8];
;     for (int e = 0; e < 8; ++e) ra[e] = of[e] * rs * p.dn_norm_g[li * 128 + ((c0 + e) & 127)] * siluf_(bf2f((bfu)z[e]));
;     uint4 wa; wa.x = pack2(ra[0], ra[1]); wa.y = pack2(ra[2], ra[3]); wa.z = pack2(ra[4], ra[5]); wa.w = pack2(ra[6], ra[7]);
;     *(uint4*)(pr + 512 + c0) = wa;
;     }
.LBB0_251:
	v_lshl_add_u64 v[68:69], v[20:21], 0, s[22:23]
	v_lshl_add_u64 v[70:71], v[68:69], 0, s[22:23]
	v_lshl_add_u64 v[72:73], v[70:71], 0, s[22:23]
	global_load_dwordx4 v[2:5], v[20:21], off
	global_load_dwordx4 v[14:17], v[20:21], off offset:3072
	global_load_dwordx4 v[10:13], v[18:19], off
	global_load_dwordx4 v[6:9], v[18:19], off offset:16
	global_load_dwordx4 v[52:55], v[68:69], off
	global_load_dwordx4 v[64:67], v[68:69], off offset:3072
	global_load_dwordx4 v[60:63], v[18:19], off
	global_load_dwordx4 v[56:59], v[18:19], off offset:16
	global_load_dwordx4 v[102:105], v[70:71], off
	global_load_dwordx4 v[114:117], v[70:71], off offset:3072
	global_load_dwordx4 v[110:113], v[18:19], off
	global_load_dwordx4 v[106:109], v[18:19], off offset:16
	global_load_dwordx4 v[152:155], v[72:73], off
	global_load_dwordx4 v[164:167], v[72:73], off offset:3072
	global_load_dwordx4 v[160:163], v[18:19], off
	global_load_dwordx4 v[156:159], v[18:19], off offset:16
	v_add_u32_e32 v0, 32, v0
	v_cmp_lt_i32_e32 vcc, s20, v0
	s_or_b64 s[12:13], vcc, s[12:13]
	s_waitcnt vmcnt(12)
	v_lshlrev_b32_e32 v27, 16, v3
	v_lshlrev_b32_e32 v26, 16, v2
	v_and_b32_e32 v3, 0xffff0000, v3
	v_and_b32_e32 v2, 0xffff0000, v2
	v_mov_b32_e32 v34, v6
	v_mov_b32_e32 v35, v8
	v_mov_b32_e32 v8, v7
	v_pk_mul_f32 v[6:7], v[26:27], v[26:27]
	v_pk_mul_f32 v[36:37], v[2:3], v[2:3]
	v_mov_b32_e32 v30, v10
	v_lshlrev_b32_e32 v10, 16, v4
	v_and_b32_e32 v4, 0xffff0000, v4
	v_add_f32_e32 v6, v6, v36
	v_mov_b32_e32 v38, v4
	v_mov_b32_e32 v39, v10
	v_add_f32_e32 v6, v7, v6
	v_mov_b32_e32 v31, v12
	v_mov_b32_e32 v12, v11
	v_lshlrev_b32_e32 v11, 16, v5
	v_and_b32_e32 v5, 0xffff0000, v5
	v_pk_mul_f32 v[38:39], v[38:39], v[38:39]
	v_add_f32_e32 v6, v37, v6
	v_mov_b32_e32 v40, v5
	v_mov_b32_e32 v41, v11
	v_add_f32_e32 v6, v39, v6
	v_pk_mul_f32 v[40:41], v[40:41], v[40:41]
	v_add_f32_e32 v6, v38, v6
	v_add_f32_e32 v6, v41, v6
	v_add_f32_e32 v6, v40, v6
	ds_bpermute_b32 v36, v22, v6
	v_lshlrev_b32_e32 v29, 16, v15
	v_and_b32_e32 v15, 0xffff0000, v15
	v_mul_f32_e32 v45, 0xbfb8aa3b, v15
	v_exp_f32_e32 v45, v45
	s_waitcnt lgkmcnt(0)
	v_add_f32_e32 v36, v6, v36
	ds_bpermute_b32 v41, v23, v36
	v_lshlrev_b32_e32 v28, 16, v14
	v_lshlrev_b32_e32 v32, 16, v16
	v_add_f32_e32 v39, 1.0, v45
	v_mul_f32_e32 v42, 0xbfb8aa3b, v28
	s_waitcnt lgkmcnt(0)
	v_add_f32_e32 v41, v36, v41
	ds_bpermute_b32 v45, v24, v41
	v_mul_f32_e32 v44, 0xbfb8aa3b, v29
	v_mul_f32_e32 v46, 0xbfb8aa3b, v32
	v_exp_f32_e32 v42, v42
	v_exp_f32_e32 v44, v44
	v_exp_f32_e32 v46, v46
	s_waitcnt lgkmcnt(0)
	v_add_f32_e32 v45, v41, v45
	v_add_f32_e32 v7, 1.0, v42
	v_add_f32_e32 v38, 1.0, v44
	v_add_f32_e32 v40, 1.0, v46
	ds_bpermute_b32 v46, v25, v45
	v_and_b32_e32 v14, 0xffff0000, v14
	v_lshlrev_b32_e32 v33, 16, v17
	v_and_b32_e32 v17, 0xffff0000, v17
	v_and_b32_e32 v16, 0xffff0000, v16
	v_rcp_f32_e32 v6, v7
	v_rcp_f32_e32 v7, v38
	v_mul_f32_e32 v43, 0xbfb8aa3b, v14
	v_mul_f32_e32 v47, 0xbfb8aa3b, v16
	v_mul_f32_e32 v49, 0xbfb8aa3b, v17
	v_mul_f32_e32 v48, 0xbfb8aa3b, v33
	v_exp_f32_e32 v43, v43
	v_exp_f32_e32 v47, v47
	v_exp_f32_e32 v49, v49
	v_exp_f32_e32 v48, v48
	v_pk_mul_f32 v[6:7], v[6:7], v[28:29]
	s_waitcnt lgkmcnt(0)
	v_add_f32_e32 v28, v45, v46
	v_fmamk_f32 v28, v28, 0x3c000000, v201
	v_add_f32_e32 v37, 1.0, v43
	v_add_f32_e32 v42, 1.0, v47
	v_add_f32_e32 v44, 1.0, v49
	v_rsq_f32_e32 v28, v28
	v_add_f32_e32 v43, 1.0, v48
	v_rcp_f32_e32 v36, v37
	v_rcp_f32_e32 v37, v39
	v_rcp_f32_e32 v38, v40
	v_rcp_f32_e32 v40, v42
	v_rcp_f32_e32 v41, v44
	v_rcp_f32_e32 v39, v43
	v_pk_mul_f32 v[2:3], v[28:29], v[2:3] op_sel_hi:[0,1]
	v_pk_mul_f32 v[4:5], v[28:29], v[4:5] op_sel_hi:[0,1]
	v_pk_mul_f32 v[14:15], v[36:37], v[14:15]
	v_pk_mul_f32 v[16:17], v[40:41], v[16:17]
	v_pk_mul_f32 v[26:27], v[28:29], v[26:27] op_sel_hi:[0,1]
	v_pk_mul_f32 v[10:11], v[28:29], v[10:11] op_sel_hi:[0,1]
	v_pk_mul_f32 v[2:3], v[12:13], v[2:3]
	v_pk_mul_f32 v[4:5], v[8:9], v[4:5]
	v_pk_mul_f32 v[32:33], v[38:39], v[32:33]
	v_pk_mul_f32 v[26:27], v[30:31], v[26:27]
	v_pk_mul_f32 v[10:11], v[34:35], v[10:11]
	v_pk_mul_f32 v[2:3], v[14:15], v[2:3]
	v_pk_mul_f32 v[4:5], v[16:17], v[4:5]
	v_pk_mul_f32 v[6:7], v[6:7], v[26:27]
	v_pk_mul_f32 v[8:9], v[32:33], v[10:11]
	v_and_b32_sdwa v12, v3, v220 dst_sel:DWORD dst_unused:UNUSED_PAD src0_sel:WORD_1 src1_sel:DWORD
	v_and_b32_sdwa v13, v2, v220 dst_sel:DWORD dst_unused:UNUSED_PAD src0_sel:WORD_1 src1_sel:DWORD
	v_and_b32_sdwa v16, v5, v220 dst_sel:DWORD dst_unused:UNUSED_PAD src0_sel:WORD_1 src1_sel:DWORD
	v_and_b32_sdwa v17, v4, v220 dst_sel:DWORD dst_unused:UNUSED_PAD src0_sel:WORD_1 src1_sel:DWORD
	v_and_b32_sdwa v10, v7, v220 dst_sel:DWORD dst_unused:UNUSED_PAD src0_sel:WORD_1 src1_sel:DWORD
	v_and_b32_sdwa v11, v6, v220 dst_sel:DWORD dst_unused:UNUSED_PAD src0_sel:WORD_1 src1_sel:DWORD
	v_and_b32_sdwa v14, v9, v220 dst_sel:DWORD dst_unused:UNUSED_PAD src0_sel:WORD_1 src1_sel:DWORD
	v_and_b32_sdwa v15, v8, v220 dst_sel:DWORD dst_unused:UNUSED_PAD src0_sel:WORD_1 src1_sel:DWORD
	v_add3_u32 v3, v3, v12, s72
	v_add3_u32 v2, v2, v13, s72
	v_add3_u32 v5, v5, v16, s72
	v_add3_u32 v4, v4, v17, s72
	v_add3_u32 v6, v6, v11, s72
	v_add3_u32 v7, v7, v10, s72
	v_add3_u32 v8, v8, v15, s72
	v_add3_u32 v9, v9, v14, s72
	v_and_b32_e32 v3, 0xffff0000, v3
	v_and_b32_e32 v2, 0xffff0000, v2
	v_and_b32_e32 v5, 0xffff0000, v5
	v_and_b32_e32 v4, 0xffff0000, v4
	v_or_b32_sdwa v3, v3, v7 dst_sel:DWORD dst_unused:UNUSED_PAD src0_sel:DWORD src1_sel:WORD_1
	v_or_b32_sdwa v2, v2, v6 dst_sel:DWORD dst_unused:UNUSED_PAD src0_sel:DWORD src1_sel:WORD_1
	v_or_b32_sdwa v5, v5, v9 dst_sel:DWORD dst_unused:UNUSED_PAD src0_sel:DWORD src1_sel:WORD_1
	v_or_b32_sdwa v4, v4, v8 dst_sel:DWORD dst_unused:UNUSED_PAD src0_sel:DWORD src1_sel:WORD_1
	global_store_dwordx4 v[20:21], v[2:5], off offset:1024
	s_waitcnt vmcnt(9)
; __device__ __forceinline__ float bf2f(bfu h) { return __uint_as_float(((unsigned)h) << 16); }
; __device__ __forceinline__ unsigned pack2(float a, float b) { return (unsigned)f2bf(a) | ((unsigned)f2bf(b) << 16); }
; __device__ __forceinline__ float frsq(float x) { return __builtin_amdgcn_rsqf(x); }
; __device__ __forceinline__ float siluf_(float x) { return x * frcp(1.0f + fexp(-x)); }
; #define SHX(v, m) shx_((v), (m), lane)
; __device__ void ab_fin_rows(const Params& p, int L, int row0, int nrows, const bool doA, const bool doB) {
;     ...
;     if (doA) {
;     bf16x8 o = *(const bf16x8*)(pr + c0);
;     bf16x8 z = *(const bf16x8*)(pr + 1536 + c0);
;     float of[8]; float ss = 0.f;
;     for (int e = 0; e < 8; ++e) { of[e] = bf2f((bfu)o[e]); ss += of[e] * of[e]; }
;     ss += SHX(ss, 1); ss += SHX(ss, 2); ss += SHX(ss, 4); ss += SHX(ss, 8);
;     const float rs = frsq(ss * (1.0f / 128.0f) + 1e-6f);
;     float ra[8];
;     for (int e = 0; e < 8; ++e) ra[e] = of[e] * rs * p.dn_norm_g[li * 128 + ((c0 + e) & 127)] * siluf_(bf2f((bfu)z[e]));
;     uint4 wa; wa.x = pack2(ra[0], ra[1]); wa.y = pack2(ra[2], ra[3]); wa.z = pack2(ra[4], ra[5]); wa.w = pack2(ra[6], ra[7]);
;     *(uint4*)(pr + 512 + c0) = wa;
;     }
	v_lshlrev_b32_e32 v77, 16, v53
	v_lshlrev_b32_e32 v76, 16, v52
	v_and_b32_e32 v53, 0xffff0000, v53
	v_and_b32_e32 v52, 0xffff0000, v52
	v_mov_b32_e32 v84, v56
	v_mov_b32_e32 v85, v58
	v_mov_b32_e32 v58, v57
	v_pk_mul_f32 v[56:57], v[76:77], v[76:77]
	v_pk_mul_f32 v[86:87], v[52:53], v[52:53]
	v_mov_b32_e32 v80, v60
	v_lshlrev_b32_e32 v60, 16, v54
	v_and_b32_e32 v54, 0xffff0000, v54
	v_add_f32_e32 v56, v56, v86
	v_mov_b32_e32 v88, v54
	v_mov_b32_e32 v89, v60
	v_add_f32_e32 v56, v57, v56
	v_mov_b32_e32 v81, v62
	v_mov_b32_e32 v62, v61
	v_lshlrev_b32_e32 v61, 16, v55
	v_and_b32_e32 v55, 0xffff0000, v55
	v_pk_mul_f32 v[88:89], v[88:89], v[88:89]
	v_add_f32_e32 v56, v87, v56
	v_mov_b32_e32 v90, v55
	v_mov_b32_e32 v91, v61
	v_add_f32_e32 v56, v89, v56
	v_pk_mul_f32 v[90:91], v[90:91], v[90:91]
	v_add_f32_e32 v56, v88, v56
	v_add_f32_e32 v56, v91, v56
	v_add_f32_e32 v56, v90, v56
	ds_bpermute_b32 v86, v22, v56
	v_lshlrev_b32_e32 v79, 16, v65
	v_and_b32_e32 v65, 0xffff0000, v65
	v_mul_f32_e32 v95, 0xbfb8aa3b, v65
	v_exp_f32_e32 v95, v95
	s_waitcnt lgkmcnt(0)
	v_add_f32_e32 v86, v56, v86
	ds_bpermute_b32 v91, v23, v86
	v_lshlrev_b32_e32 v78, 16, v64
	v_lshlrev_b32_e32 v82, 16, v66
	v_add_f32_e32 v89, 1.0, v95
	v_mul_f32_e32 v92, 0xbfb8aa3b, v78
	s_waitcnt lgkmcnt(0)
	v_add_f32_e32 v91, v86, v91
	ds_bpermute_b32 v95, v24, v91
	v_mul_f32_e32 v94, 0xbfb8aa3b, v79
	v_mul_f32_e32 v96, 0xbfb8aa3b, v82
	v_exp_f32_e32 v92, v92
	v_exp_f32_e32 v94, v94
	v_exp_f32_e32 v96, v96
	s_waitcnt lgkmcnt(0)
	v_add_f32_e32 v95, v91, v95
	v_add_f32_e32 v57, 1.0, v92
	v_add_f32_e32 v88, 1.0, v94
	v_add_f32_e32 v90, 1.0, v96
	ds_bpermute_b32 v96, v25, v95
	v_and_b32_e32 v64, 0xffff0000, v64
	v_lshlrev_b32_e32 v83, 16, v67
	v_and_b32_e32 v67, 0xffff0000, v67
	v_and_b32_e32 v66, 0xffff0000, v66
	v_rcp_f32_e32 v56, v57
	v_rcp_f32_e32 v57, v88
	v_mul_f32_e32 v93, 0xbfb8aa3b, v64
	v_mul_f32_e32 v97, 0xbfb8aa3b, v66
	v_mul_f32_e32 v99, 0xbfb8aa3b, v67
	v_mul_f32_e32 v98, 0xbfb8aa3b, v83
	v_exp_f32_e32 v93, v93
	v_exp_f32_e32 v97, v97
	v_exp_f32_e32 v99, v99
	v_exp_f32_e32 v98, v98
	v_pk_mul_f32 v[56:57], v[56:57], v[78:79]
	s_waitcnt lgkmcnt(0)
	v_add_f32_e32 v78, v95, v96
	v_fmamk_f32 v78, v78, 0x3c000000, v201
	v_add_f32_e32 v87, 1.0, v93
	v_add_f32_e32 v92, 1.0, v97
	v_add_f32_e32 v94, 1.0, v99
	v_rsq_f32_e32 v78, v78
	v_add_f32_e32 v93, 1.0, v98
	v_rcp_f32_e32 v86, v87
	v_rcp_f32_e32 v87, v89
	v_rcp_f32_e32 v88, v90
	v_rcp_f32_e32 v90, v92
	v_rcp_f32_e32 v91, v94
	v_rcp_f32_e32 v89, v93
	v_pk_mul_f32 v[52:53], v[78:79], v[52:53] op_sel_hi:[0,1]
	v_pk_mul_f32 v[54:55], v[78:79], v[54:55] op_sel_hi:[0,1]
	v_pk_mul_f32 v[64:65], v[86:87], v[64:65]
	v_pk_mul_f32 v[66:67], v[90:91], v[66:67]
	v_pk_mul_f32 v[76:77], v[78:79], v[76:77] op_sel_hi:[0,1]
	v_pk_mul_f32 v[60:61], v[78:79], v[60:61] op_sel_hi:[0,1]
	v_pk_mul_f32 v[52:53], v[62:63], v[52:53]
	v_pk_mul_f32 v[54:55], v[58:59], v[54:55]
	v_pk_mul_f32 v[82:83], v[88:89], v[82:83]
	v_pk_mul_f32 v[76:77], v[80:81], v[76:77]
	v_pk_mul_f32 v[60:61], v[84:85], v[60:61]
	v_pk_mul_f32 v[52:53], v[64:65], v[52:53]
	v_pk_mul_f32 v[54:55], v[66:67], v[54:55]
	v_pk_mul_f32 v[56:57], v[56:57], v[76:77]
	v_pk_mul_f32 v[58:59], v[82:83], v[60:61]
	v_and_b32_sdwa v62, v53, v220 dst_sel:DWORD dst_unused:UNUSED_PAD src0_sel:WORD_1 src1_sel:DWORD
	v_and_b32_sdwa v63, v52, v220 dst_sel:DWORD dst_unused:UNUSED_PAD src0_sel:WORD_1 src1_sel:DWORD
	v_and_b32_sdwa v66, v55, v220 dst_sel:DWORD dst_unused:UNUSED_PAD src0_sel:WORD_1 src1_sel:DWORD
	v_and_b32_sdwa v67, v54, v220 dst_sel:DWORD dst_unused:UNUSED_PAD src0_sel:WORD_1 src1_sel:DWORD
	v_and_b32_sdwa v60, v57, v220 dst_sel:DWORD dst_unused:UNUSED_PAD src0_sel:WORD_1 src1_sel:DWORD
	v_and_b32_sdwa v61, v56, v220 dst_sel:DWORD dst_unused:UNUSED_PAD src0_sel:WORD_1 src1_sel:DWORD
	v_and_b32_sdwa v64, v59, v220 dst_sel:DWORD dst_unused:UNUSED_PAD src0_sel:WORD_1 src1_sel:DWORD
	v_and_b32_sdwa v65, v58, v220 dst_sel:DWORD dst_unused:UNUSED_PAD src0_sel:WORD_1 src1_sel:DWORD
	v_add3_u32 v53, v53, v62, s72
	v_add3_u32 v52, v52, v63, s72
	v_add3_u32 v55, v55, v66, s72
	v_add3_u32 v54, v54, v67, s72
	v_add3_u32 v56, v56, v61, s72
	v_add3_u32 v57, v57, v60, s72
	v_add3_u32 v58, v58, v65, s72
	v_add3_u32 v59, v59, v64, s72
	v_and_b32_e32 v53, 0xffff0000, v53
	v_and_b32_e32 v52, 0xffff0000, v52
	v_and_b32_e32 v55, 0xffff0000, v55
	v_and_b32_e32 v54, 0xffff0000, v54
	v_or_b32_sdwa v53, v53, v57 dst_sel:DWORD dst_unused:UNUSED_PAD src0_sel:DWORD src1_sel:WORD_1
	v_or_b32_sdwa v52, v52, v56 dst_sel:DWORD dst_unused:UNUSED_PAD src0_sel:DWORD src1_sel:WORD_1
	v_or_b32_sdwa v55, v55, v59 dst_sel:DWORD dst_unused:UNUSED_PAD src0_sel:DWORD src1_sel:WORD_1
	v_or_b32_sdwa v54, v54, v58 dst_sel:DWORD dst_unused:UNUSED_PAD src0_sel:DWORD src1_sel:WORD_1
	global_store_dwordx4 v[68:69], v[52:55], off offset:1024
	s_waitcnt vmcnt(6)
	v_lshlrev_b32_e32 v127, 16, v103
	v_lshlrev_b32_e32 v126, 16, v102
	v_and_b32_e32 v103, 0xffff0000, v103
	v_and_b32_e32 v102, 0xffff0000, v102
	v_mov_b32_e32 v134, v106
	v_mov_b32_e32 v135, v108
	v_mov_b32_e32 v108, v107
	v_pk_mul_f32 v[106:107], v[126:127], v[126:127]
	v_pk_mul_f32 v[136:137], v[102:103], v[102:103]
	v_mov_b32_e32 v130, v110
	v_lshlrev_b32_e32 v110, 16, v104
	v_and_b32_e32 v104, 0xffff0000, v104
	v_add_f32_e32 v106, v106, v136
	v_mov_b32_e32 v138, v104
	v_mov_b32_e32 v139, v110
	v_add_f32_e32 v106, v107, v106
	v_mov_b32_e32 v131, v112
	v_mov_b32_e32 v112, v111
	v_lshlrev_b32_e32 v111, 16, v105
	v_and_b32_e32 v105, 0xffff0000, v105
	v_pk_mul_f32 v[138:139], v[138:139], v[138:139]
	v_add_f32_e32 v106, v137, v106
	v_mov_b32_e32 v140, v105
	v_mov_b32_e32 v141, v111
	v_add_f32_e32 v106, v139, v106
	v_pk_mul_f32 v[140:141], v[140:141], v[140:141]
	v_add_f32_e32 v106, v138, v106
	v_add_f32_e32 v106, v141, v106
	v_add_f32_e32 v106, v140, v106
	ds_bpermute_b32 v136, v22, v106
	v_lshlrev_b32_e32 v129, 16, v115
	v_and_b32_e32 v115, 0xffff0000, v115
	v_mul_f32_e32 v145, 0xbfb8aa3b, v115
	v_exp_f32_e32 v145, v145
	s_waitcnt lgkmcnt(0)
; __device__ __forceinline__ float bf2f(bfu h) { return __uint_as_float(((unsigned)h) << 16); }
; __device__ __forceinline__ unsigned pack2(float a, float b) { return (unsigned)f2bf(a) | ((unsigned)f2bf(b) << 16); }
; __device__ __forceinline__ float frsq(float x) { return __builtin_amdgcn_rsqf(x); }
; __device__ __forceinline__ float siluf_(float x) { return x * frcp(1.0f + fexp(-x)); }
; #define SHX(v, m) shx_((v), (m), lane)
; __device__ void ab_fin_rows(const Params& p, int L, int row0, int nrows, const bool doA, const bool doB) {
;     ...
;     if (doA) {
;     bf16x8 o = *(const bf16x8*)(pr + c0);
;     bf16x8 z = *(const bf16x8*)(pr + 1536 + c0);
;     float of[8]; float ss = 0.f;
;     for (int e = 0; e < 8; ++e) { of[e] = bf2f((bfu)o[e]); ss += of[e] * of[e]; }
;     ss += SHX(ss, 1); ss += SHX(ss, 2); ss += SHX(ss, 4); ss += SHX(ss, 8);
;     const float rs = frsq(ss * (1.0f / 128.0f) + 1e-6f);
;     float ra[8];
;     for (int e = 0; e < 8; ++e) ra[e] = of[e] * rs * p.dn_norm_g[li * 128 + ((c0 + e) & 127)] * siluf_(bf2f((bfu)z[e]));
;     uint4 wa; wa.x = pack2(ra[0], ra[1]); wa.y = pack2(ra[2], ra[3]); wa.z = pack2(ra[4], ra[5]); wa.w = pack2(ra[6], ra[7]);
;     *(uint4*)(pr + 512 + c0) = wa;
;     }
	v_add_f32_e32 v136, v106, v136
	ds_bpermute_b32 v141, v23, v136
	v_lshlrev_b32_e32 v128, 16, v114
	v_lshlrev_b32_e32 v132, 16, v116
	v_add_f32_e32 v139, 1.0, v145
	v_mul_f32_e32 v142, 0xbfb8aa3b, v128
	s_waitcnt lgkmcnt(0)
	v_add_f32_e32 v141, v136, v141
	ds_bpermute_b32 v145, v24, v141
	v_mul_f32_e32 v144, 0xbfb8aa3b, v129
	v_mul_f32_e32 v146, 0xbfb8aa3b, v132
	v_exp_f32_e32 v142, v142
	v_exp_f32_e32 v144, v144
	v_exp_f32_e32 v146, v146
	s_waitcnt lgkmcnt(0)
	v_add_f32_e32 v145, v141, v145
	v_add_f32_e32 v107, 1.0, v142
	v_add_f32_e32 v138, 1.0, v144
	v_add_f32_e32 v140, 1.0, v146
	ds_bpermute_b32 v146, v25, v145
	v_and_b32_e32 v114, 0xffff0000, v114
	v_lshlrev_b32_e32 v133, 16, v117
	v_and_b32_e32 v117, 0xffff0000, v117
	v_and_b32_e32 v116, 0xffff0000, v116
	v_rcp_f32_e32 v106, v107
	v_rcp_f32_e32 v107, v138
	v_mul_f32_e32 v143, 0xbfb8aa3b, v114
	v_mul_f32_e32 v147, 0xbfb8aa3b, v116
	v_mul_f32_e32 v149, 0xbfb8aa3b, v117
	v_mul_f32_e32 v148, 0xbfb8aa3b, v133
	v_exp_f32_e32 v143, v143
	v_exp_f32_e32 v147, v147
	v_exp_f32_e32 v149, v149
	v_exp_f32_e32 v148, v148
	v_pk_mul_f32 v[106:107], v[106:107], v[128:129]
	s_waitcnt lgkmcnt(0)
	v_add_f32_e32 v128, v145, v146
	v_fmamk_f32 v128, v128, 0x3c000000, v201
	v_add_f32_e32 v137, 1.0, v143
	v_add_f32_e32 v142, 1.0, v147
	v_add_f32_e32 v144, 1.0, v149
	v_rsq_f32_e32 v128, v128
	v_add_f32_e32 v143, 1.0, v148
	v_rcp_f32_e32 v136, v137
	v_rcp_f32_e32 v137, v139
	v_rcp_f32_e32 v138, v140
	v_rcp_f32_e32 v140, v142
	v_rcp_f32_e32 v141, v144
	v_rcp_f32_e32 v139, v143
	v_pk_mul_f32 v[102:103], v[128:129], v[102:103] op_sel_hi:[0,1]
	v_pk_mul_f32 v[104:105], v[128:129], v[104:105] op_sel_hi:[0,1]
	v_pk_mul_f32 v[114:115], v[136:137], v[114:115]
	v_pk_mul_f32 v[116:117], v[140:141], v[116:117]
	v_pk_mul_f32 v[126:127], v[128:129], v[126:127] op_sel_hi:[0,1]
	v_pk_mul_f32 v[110:111], v[128:129], v[110:111] op_sel_hi:[0,1]
	v_pk_mul_f32 v[102:103], v[112:113], v[102:103]
	v_pk_mul_f32 v[104:105], v[108:109], v[104:105]
	v_pk_mul_f32 v[132:133], v[138:139], v[132:133]
	v_pk_mul_f32 v[126:127], v[130:131], v[126:127]
	v_pk_mul_f32 v[110:111], v[134:135], v[110:111]
	v_pk_mul_f32 v[102:103], v[114:115], v[102:103]
	v_pk_mul_f32 v[104:105], v[116:117], v[104:105]
	v_pk_mul_f32 v[106:107], v[106:107], v[126:127]
	v_pk_mul_f32 v[108:109], v[132:133], v[110:111]
	v_and_b32_sdwa v112, v103, v220 dst_sel:DWORD dst_unused:UNUSED_PAD src0_sel:WORD_1 src1_sel:DWORD
	v_and_b32_sdwa v113, v102, v220 dst_sel:DWORD dst_unused:UNUSED_PAD src0_sel:WORD_1 src1_sel:DWORD
	v_and_b32_sdwa v116, v105, v220 dst_sel:DWORD dst_unused:UNUSED_PAD src0_sel:WORD_1 src1_sel:DWORD
	v_and_b32_sdwa v117, v104, v220 dst_sel:DWORD dst_unused:UNUSED_PAD src0_sel:WORD_1 src1_sel:DWORD
	v_and_b32_sdwa v110, v107, v220 dst_sel:DWORD dst_unused:UNUSED_PAD src0_sel:WORD_1 src1_sel:DWORD
	v_and_b32_sdwa v111, v106, v220 dst_sel:DWORD dst_unused:UNUSED_PAD src0_sel:WORD_1 src1_sel:DWORD
	v_and_b32_sdwa v114, v109, v220 dst_sel:DWORD dst_unused:UNUSED_PAD src0_sel:WORD_1 src1_sel:DWORD
	v_and_b32_sdwa v115, v108, v220 dst_sel:DWORD dst_unused:UNUSED_PAD src0_sel:WORD_1 src1_sel:DWORD
	v_add3_u32 v103, v103, v112, s72
	v_add3_u32 v102, v102, v113, s72
	v_add3_u32 v105, v105, v116, s72
	v_add3_u32 v104, v104, v117, s72
	v_add3_u32 v106, v106, v111, s72
	v_add3_u32 v107, v107, v110, s72
	v_add3_u32 v108, v108, v115, s72
	v_add3_u32 v109, v109, v114, s72
	v_and_b32_e32 v103, 0xffff0000, v103
	v_and_b32_e32 v102, 0xffff0000, v102
	v_and_b32_e32 v105, 0xffff0000, v105
	v_and_b32_e32 v104, 0xffff0000, v104
	v_or_b32_sdwa v103, v103, v107 dst_sel:DWORD dst_unused:UNUSED_PAD src0_sel:DWORD src1_sel:WORD_1
	v_or_b32_sdwa v102, v102, v106 dst_sel:DWORD dst_unused:UNUSED_PAD src0_sel:DWORD src1_sel:WORD_1
	v_or_b32_sdwa v105, v105, v109 dst_sel:DWORD dst_unused:UNUSED_PAD src0_sel:DWORD src1_sel:WORD_1
	v_or_b32_sdwa v104, v104, v108 dst_sel:DWORD dst_unused:UNUSED_PAD src0_sel:DWORD src1_sel:WORD_1
	global_store_dwordx4 v[70:71], v[102:105], off offset:1024
	s_waitcnt vmcnt(3)
	v_lshlrev_b32_e32 v177, 16, v153
	v_lshlrev_b32_e32 v176, 16, v152
	v_and_b32_e32 v153, 0xffff0000, v153
	v_and_b32_e32 v152, 0xffff0000, v152
	v_mov_b32_e32 v184, v156
	v_mov_b32_e32 v185, v158
	v_mov_b32_e32 v158, v157
	v_pk_mul_f32 v[156:157], v[176:177], v[176:177]
	v_pk_mul_f32 v[186:187], v[152:153], v[152:153]
	v_mov_b32_e32 v180, v160
	v_lshlrev_b32_e32 v160, 16, v154
	v_and_b32_e32 v154, 0xffff0000, v154
	v_add_f32_e32 v156, v156, v186
	v_mov_b32_e32 v188, v154
	v_mov_b32_e32 v189, v160
	v_add_f32_e32 v156, v157, v156
	v_mov_b32_e32 v181, v162
	v_mov_b32_e32 v162, v161
	v_lshlrev_b32_e32 v161, 16, v155
	v_and_b32_e32 v155, 0xffff0000, v155
	v_pk_mul_f32 v[188:189], v[188:189], v[188:189]
	v_add_f32_e32 v156, v187, v156
	v_mov_b32_e32 v190, v155
	v_mov_b32_e32 v191, v161
	v_add_f32_e32 v156, v189, v156
	v_pk_mul_f32 v[190:191], v[190:191], v[190:191]
	v_add_f32_e32 v156, v188, v156
	v_add_f32_e32 v156, v191, v156
	v_add_f32_e32 v156, v190, v156
	ds_bpermute_b32 v186, v22, v156
	v_lshlrev_b32_e32 v179, 16, v165
	v_and_b32_e32 v165, 0xffff0000, v165
	v_mul_f32_e32 v195, 0xbfb8aa3b, v165
	v_exp_f32_e32 v195, v195
	s_waitcnt lgkmcnt(0)
; __device__ __forceinline__ float bf2f(bfu h) { return __uint_as_float(((unsigned)h) << 16); }
; __device__ __forceinline__ unsigned pack2(float a, float b) { return (unsigned)f2bf(a) | ((unsigned)f2bf(b) << 16); }
; __device__ __forceinline__ float frsq(float x) { return __builtin_amdgcn_rsqf(x); }
; __device__ __forceinline__ float siluf_(float x) { return x * frcp(1.0f + fexp(-x)); }
; #define SHX(v, m) shx_((v), (m), lane)
; __device__ void ab_fin_rows(const Params& p, int L, int row0, int nrows, const bool doA, const bool doB) {
;     ...
;     if (doA) {
;     bf16x8 o = *(const bf16x8*)(pr + c0);
;     bf16x8 z = *(const bf16x8*)(pr + 1536 + c0);
;     float of[8]; float ss = 0.f;
;     for (int e = 0; e < 8; ++e) { of[e] = bf2f((bfu)o[e]); ss += of[e] * of[e]; }
;     ss += SHX(ss, 1); ss += SHX(ss, 2); ss += SHX(ss, 4); ss += SHX(ss, 8);
;     const float rs = frsq(ss * (1.0f / 128.0f) + 1e-6f);
;     float ra[8];
;     for (int e = 0; e < 8; ++e) ra[e] = of[e] * rs * p.dn_norm_g[li * 128 + ((c0 + e) & 127)] * siluf_(bf2f((bfu)z[e]));
;     uint4 wa; wa.x = pack2(ra[0], ra[1]); wa.y = pack2(ra[2], ra[3]); wa.z = pack2(ra[4], ra[5]); wa.w = pack2(ra[6], ra[7]);
;     *(uint4*)(pr + 512 + c0) = wa;
;     }
	v_add_f32_e32 v186, v156, v186
	ds_bpermute_b32 v191, v23, v186
	v_lshlrev_b32_e32 v178, 16, v164
	v_lshlrev_b32_e32 v182, 16, v166
	v_add_f32_e32 v189, 1.0, v195
	v_mul_f32_e32 v192, 0xbfb8aa3b, v178
	s_waitcnt lgkmcnt(0)
	v_add_f32_e32 v191, v186, v191
	ds_bpermute_b32 v195, v24, v191
	v_mul_f32_e32 v194, 0xbfb8aa3b, v179
	v_mul_f32_e32 v196, 0xbfb8aa3b, v182
	v_exp_f32_e32 v192, v192
	v_exp_f32_e32 v194, v194
	v_exp_f32_e32 v196, v196
	s_waitcnt lgkmcnt(0)
	v_add_f32_e32 v195, v191, v195
	v_add_f32_e32 v157, 1.0, v192
	v_add_f32_e32 v188, 1.0, v194
	v_add_f32_e32 v190, 1.0, v196
	ds_bpermute_b32 v196, v25, v195
	v_and_b32_e32 v164, 0xffff0000, v164
	v_lshlrev_b32_e32 v183, 16, v167
	v_and_b32_e32 v167, 0xffff0000, v167
	v_and_b32_e32 v166, 0xffff0000, v166
	v_rcp_f32_e32 v156, v157
	v_rcp_f32_e32 v157, v188
	v_mul_f32_e32 v193, 0xbfb8aa3b, v164
	v_mul_f32_e32 v197, 0xbfb8aa3b, v166
	v_mul_f32_e32 v199, 0xbfb8aa3b, v167
	v_mul_f32_e32 v198, 0xbfb8aa3b, v183
	v_exp_f32_e32 v193, v193
	v_exp_f32_e32 v197, v197
	v_exp_f32_e32 v199, v199
	v_exp_f32_e32 v198, v198
	v_pk_mul_f32 v[156:157], v[156:157], v[178:179]
	s_waitcnt lgkmcnt(0)
	v_add_f32_e32 v178, v195, v196
	v_fmamk_f32 v178, v178, 0x3c000000, v201
	v_add_f32_e32 v187, 1.0, v193
	v_add_f32_e32 v192, 1.0, v197
	v_add_f32_e32 v194, 1.0, v199
	v_rsq_f32_e32 v178, v178
	v_add_f32_e32 v193, 1.0, v198
	v_rcp_f32_e32 v186, v187
	v_rcp_f32_e32 v187, v189
	v_rcp_f32_e32 v188, v190
	v_rcp_f32_e32 v190, v192
	v_rcp_f32_e32 v191, v194
	v_rcp_f32_e32 v189, v193
	v_pk_mul_f32 v[152:153], v[178:179], v[152:153] op_sel_hi:[0,1]
	v_pk_mul_f32 v[154:155], v[178:179], v[154:155] op_sel_hi:[0,1]
	v_pk_mul_f32 v[164:165], v[186:187], v[164:165]
	v_pk_mul_f32 v[166:167], v[190:191], v[166:167]
	v_pk_mul_f32 v[176:177], v[178:179], v[176:177] op_sel_hi:[0,1]
	v_pk_mul_f32 v[160:161], v[178:179], v[160:161] op_sel_hi:[0,1]
	v_pk_mul_f32 v[152:153], v[162:163], v[152:153]
	v_pk_mul_f32 v[154:155], v[158:159], v[154:155]
	v_pk_mul_f32 v[182:183], v[188:189], v[182:183]
	v_pk_mul_f32 v[176:177], v[180:181], v[176:177]
	v_pk_mul_f32 v[160:161], v[184:185], v[160:161]
	v_pk_mul_f32 v[152:153], v[164:165], v[152:153]
	v_pk_mul_f32 v[154:155], v[166:167], v[154:155]
	v_pk_mul_f32 v[156:157], v[156:157], v[176:177]
	v_pk_mul_f32 v[158:159], v[182:183], v[160:161]
	v_and_b32_sdwa v162, v153, v220 dst_sel:DWORD dst_unused:UNUSED_PAD src0_sel:WORD_1 src1_sel:DWORD
	v_and_b32_sdwa v163, v152, v220 dst_sel:DWORD dst_unused:UNUSED_PAD src0_sel:WORD_1 src1_sel:DWORD
	v_and_b32_sdwa v166, v155, v220 dst_sel:DWORD dst_unused:UNUSED_PAD src0_sel:WORD_1 src1_sel:DWORD
	v_and_b32_sdwa v167, v154, v220 dst_sel:DWORD dst_unused:UNUSED_PAD src0_sel:WORD_1 src1_sel:DWORD
	v_and_b32_sdwa v160, v157, v220 dst_sel:DWORD dst_unused:UNUSED_PAD src0_sel:WORD_1 src1_sel:DWORD
	v_and_b32_sdwa v161, v156, v220 dst_sel:DWORD dst_unused:UNUSED_PAD src0_sel:WORD_1 src1_sel:DWORD
	v_and_b32_sdwa v164, v159, v220 dst_sel:DWORD dst_unused:UNUSED_PAD src0_sel:WORD_1 src1_sel:DWORD
	v_and_b32_sdwa v165, v158, v220 dst_sel:DWORD dst_unused:UNUSED_PAD src0_sel:WORD_1 src1_sel:DWORD
	v_add3_u32 v153, v153, v162, s72
	v_add3_u32 v152, v152, v163, s72
	v_add3_u32 v155, v155, v166, s72
	v_add3_u32 v154, v154, v167, s72
	v_add3_u32 v156, v156, v161, s72
	v_add3_u32 v157, v157, v160, s72
	v_add3_u32 v158, v158, v165, s72
	v_add3_u32 v159, v159, v164, s72
	v_and_b32_e32 v153, 0xffff0000, v153
	v_and_b32_e32 v152, 0xffff0000, v152
	v_and_b32_e32 v155, 0xffff0000, v155
	v_and_b32_e32 v154, 0xffff0000, v154
	v_or_b32_sdwa v153, v153, v157 dst_sel:DWORD dst_unused:UNUSED_PAD src0_sel:DWORD src1_sel:WORD_1
	v_or_b32_sdwa v152, v152, v156 dst_sel:DWORD dst_unused:UNUSED_PAD src0_sel:DWORD src1_sel:WORD_1
	v_or_b32_sdwa v155, v155, v159 dst_sel:DWORD dst_unused:UNUSED_PAD src0_sel:DWORD src1_sel:WORD_1
	v_or_b32_sdwa v154, v154, v158 dst_sel:DWORD dst_unused:UNUSED_PAD src0_sel:DWORD src1_sel:WORD_1
	global_store_dwordx4 v[72:73], v[152:155], off offset:1024
	v_lshl_add_u64 v[20:21], v[72:73], 0, s[22:23]
	s_andn2_b64 exec, exec, s[12:13]
	s_cbranch_execnz .LBB0_251
	s_branch .LBB0_248
